# MLA softmax: cross-half row-max exchange via v_permlane32_swap instead of an LDS bpermute round trip; V-fragment wait moved to first use
# speedup vs baseline: 1.0655x; 1.0034x over previous
; #define MFMA(a, b, c) __builtin_amdgcn_mfma_f32_32x32x16_bf16((a), (b), (c), 0, 0, 0)
; DI float ex2(float x) { return __builtin_amdgcn_exp2f(x); }
; DI void mla_item(const Params& p, int qb, int b, int h, char* smem) {
;     ...
;       float mx = -1e30f;
; #pragma unroll
;       for (int t32 = 0; t32 < 2; ++t32)
; #pragma unroll
;         for (int r = 0; r < 16; ++r) mx = fmaxf(mx, st[t32][r]);
;       mx = fmaxf(mx, __shfl_xor(mx, 32));
;       const float mn = fmaxf(m, mx);
;       const float alpha = ex2(m - mn);
;       m = mn;
;       float ps = 0.f;
; #pragma unroll
;       for (int t32 = 0; t32 < 2; ++t32)
; #pragma unroll
;         for (int r = 0; r < 16; ++r) { const float pv = ex2(st[t32][r] - mn); st[t32][r] = pv; ps += pv; }
;       l = l * alpha + ps;
; #pragma unroll
;       for (int mt = 0; mt < 2; ++mt)
; #pragma unroll
;         for (int r = 0; r < 16; ++r) ot[mt][r] *= alpha;
;       __builtin_amdgcn_s_setprio(1);
; #pragma unroll
;       for (int t32 = 0; t32 < 2; ++t32)
; #pragma unroll
;         for (int s = 0; s < 2; ++s) {
;           const bf16x8 pf = pack8(st[t32], s);
; #pragma unroll
;           for (int mt = 0; mt < 2; ++mt) ot[mt] = MFMA(vf[t32][s][mt], pf, ot[mt]);
;         }
;       __builtin_amdgcn_s_setprio(0);
.LBB0_631:
	s_or_b64 exec, exec, s[10:11]
	v_max3_f32 v188, v48, s20, v49
	v_max3_f32 v188, v188, v50, v51
	v_max3_f32 v188, v188, v52, v53
	v_max3_f32 v188, v188, v54, v55
	v_max3_f32 v188, v188, v56, v57
	v_max3_f32 v188, v188, v58, v59
	v_max3_f32 v188, v188, v60, v61
	v_max3_f32 v188, v188, v62, v63
	v_max3_f32 v188, v188, v32, v33
	v_max3_f32 v188, v188, v34, v35
	v_max3_f32 v188, v188, v36, v37
	v_max3_f32 v188, v188, v38, v39
	v_max3_f32 v188, v188, v40, v41
	v_max3_f32 v188, v188, v42, v43
	v_max3_f32 v188, v188, v44, v45
	v_max3_f32 v188, v188, v46, v47
	v_mov_b32_e32 v189, v188
	v_mov_b32_e32 v190, v188
	s_nop 1
	v_permlane32_swap_b32_e32 v189, v190
	v_max3_f32 v188, v228, v189, v190
	v_sub_f32_e32 v48, v48, v188
	v_exp_f32_e32 v48, v48
	v_sub_f32_e32 v49, v49, v188
	v_exp_f32_e32 v49, v49
	v_sub_f32_e32 v50, v50, v188
	v_exp_f32_e32 v50, v50
	v_sub_f32_e32 v51, v51, v188
	v_exp_f32_e32 v51, v51
	v_sub_f32_e32 v52, v52, v188
	v_add_f32_e32 v190, 0, v48
	v_exp_f32_e32 v52, v52
	v_sub_f32_e32 v53, v53, v188
	v_add_f32_e32 v190, v49, v190
	v_exp_f32_e32 v53, v53
	v_sub_f32_e32 v54, v54, v188
	v_add_f32_e32 v190, v50, v190
	v_exp_f32_e32 v54, v54
	v_sub_f32_e32 v55, v55, v188
	v_add_f32_e32 v190, v51, v190
	v_exp_f32_e32 v55, v55
	v_sub_f32_e32 v56, v56, v188
	v_add_f32_e32 v190, v52, v190
	v_exp_f32_e32 v56, v56
	v_sub_f32_e32 v57, v57, v188
	v_add_f32_e32 v190, v53, v190
	v_exp_f32_e32 v57, v57
	v_sub_f32_e32 v58, v58, v188
	v_add_f32_e32 v190, v54, v190
	v_exp_f32_e32 v58, v58
	v_sub_f32_e32 v59, v59, v188
	v_add_f32_e32 v190, v55, v190
	v_exp_f32_e32 v59, v59
	v_sub_f32_e32 v60, v60, v188
	v_add_f32_e32 v190, v56, v190
	v_exp_f32_e32 v60, v60
	v_sub_f32_e32 v61, v61, v188
	v_add_f32_e32 v190, v57, v190
	v_exp_f32_e32 v61, v61
	v_sub_f32_e32 v62, v62, v188
	v_add_f32_e32 v190, v58, v190
	v_exp_f32_e32 v62, v62
	v_sub_f32_e32 v63, v63, v188
	v_add_f32_e32 v190, v59, v190
	v_exp_f32_e32 v63, v63
	v_sub_f32_e32 v32, v32, v188
	v_add_f32_e32 v190, v60, v190
	v_exp_f32_e32 v191, v32
	v_sub_f32_e32 v33, v33, v188
	v_add_f32_e32 v32, v61, v190
	v_exp_f32_e32 v190, v33
	v_sub_f32_e32 v33, v34, v188
	v_add_f32_e32 v32, v62, v32
	v_exp_f32_e32 v194, v33
	v_sub_f32_e32 v33, v35, v188
	v_add_f32_e32 v32, v63, v32
	v_exp_f32_e32 v195, v33
	v_sub_f32_e32 v33, v36, v188
	v_add_f32_e32 v32, v191, v32
	v_exp_f32_e32 v36, v33
	v_sub_f32_e32 v33, v37, v188
	v_add_f32_e32 v32, v190, v32
	v_exp_f32_e32 v37, v33
	v_sub_f32_e32 v33, v38, v188
	v_add_f32_e32 v32, v194, v32
	v_exp_f32_e32 v38, v33
	v_sub_f32_e32 v33, v39, v188
	v_add_f32_e32 v32, v195, v32
	v_exp_f32_e32 v39, v33
	v_sub_f32_e32 v33, v40, v188
	v_add_f32_e32 v32, v36, v32
	v_exp_f32_e32 v40, v33
	v_sub_f32_e32 v33, v41, v188
	v_add_f32_e32 v32, v37, v32
	v_exp_f32_e32 v41, v33
	v_sub_f32_e32 v33, v42, v188
	v_add_f32_e32 v32, v38, v32
	v_exp_f32_e32 v42, v33
	v_sub_f32_e32 v33, v43, v188
	v_add_f32_e32 v32, v39, v32
	v_exp_f32_e32 v43, v33
	v_sub_f32_e32 v33, v44, v188
	v_add_f32_e32 v32, v40, v32
	v_exp_f32_e32 v44, v33
	v_add_f32_e32 v32, v41, v32
	v_add_f32_e32 v32, v42, v32
	v_add_f32_e32 v32, v43, v32
	v_add_f32_e32 v33, v44, v32
	v_sub_f32_e32 v32, v45, v188
	v_exp_f32_e32 v45, v32
	v_sub_f32_e32 v32, v46, v188
	v_sub_f32_e32 v189, v228, v188
	v_exp_f32_e32 v46, v32
	v_sub_f32_e32 v32, v47, v188
	v_exp_f32_e32 v47, v32
	v_exp_f32_e32 v32, v189
	v_add_f32_e32 v33, v45, v33
	v_add_f32_e32 v33, v46, v33
	v_add_f32_e32 v189, v47, v33
	v_pk_mul_f32 v[30:31], v[30:31], v[32:33] op_sel_hi:[1,0]
	v_pk_mul_f32 v[28:29], v[28:29], v[32:33] op_sel_hi:[1,0]
	v_pk_mul_f32 v[26:27], v[26:27], v[32:33] op_sel_hi:[1,0]
	v_pk_mul_f32 v[24:25], v[24:25], v[32:33] op_sel_hi:[1,0]
	v_pk_mul_f32 v[22:23], v[22:23], v[32:33] op_sel_hi:[1,0]
	v_pk_mul_f32 v[20:21], v[20:21], v[32:33] op_sel_hi:[1,0]
	v_pk_mul_f32 v[18:19], v[18:19], v[32:33] op_sel_hi:[1,0]
	v_pk_mul_f32 v[16:17], v[16:17], v[32:33] op_sel_hi:[1,0]
	v_pk_mul_f32 v[14:15], v[14:15], v[32:33] op_sel_hi:[1,0]
	v_pk_mul_f32 v[12:13], v[12:13], v[32:33] op_sel_hi:[1,0]
	v_pk_mul_f32 v[10:11], v[10:11], v[32:33] op_sel_hi:[1,0]
	v_pk_mul_f32 v[8:9], v[8:9], v[32:33] op_sel_hi:[1,0]
	v_pk_mul_f32 v[6:7], v[6:7], v[32:33] op_sel_hi:[1,0]
	v_pk_mul_f32 v[4:5], v[4:5], v[32:33] op_sel_hi:[1,0]
	v_pk_mul_f32 v[2:3], v[2:3], v[32:33] op_sel_hi:[1,0]
	v_pk_mul_f32 v[0:1], v[0:1], v[32:33] op_sel_hi:[1,0]
	v_fmac_f32_e32 v189, v227, v32
	s_waitcnt lgkmcnt(0)
	s_setprio 1
	v_cvt_pk_bf16_f32 v32, v48, v49
	v_cvt_pk_bf16_f32 v33, v50, v51
	v_cvt_pk_bf16_f32 v34, v52, v53
	v_cvt_pk_bf16_f32 v35, v54, v55
	s_nop 1
	v_mfma_f32_32x32x16_bf16 v[16:31], v[152:155], v[32:35], v[16:31]
	v_mfma_f32_32x32x16_bf16 v[0:15], v[156:159], v[32:35], v[0:15]
	v_cvt_pk_bf16_f32 v32, v56, v57
	v_cvt_pk_bf16_f32 v33, v58, v59
	v_cvt_pk_bf16_f32 v34, v60, v61
	v_cvt_pk_bf16_f32 v35, v62, v63
	s_nop 1
	v_mfma_f32_32x32x16_bf16 v[16:31], v[144:147], v[32:35], v[16:31]
	v_mfma_f32_32x32x16_bf16 v[0:15], v[148:151], v[32:35], v[0:15]
	v_cvt_pk_bf16_f32 v32, v191, v190
	v_cvt_pk_bf16_f32 v33, v194, v195
	v_cvt_pk_bf16_f32 v34, v36, v37
	v_cvt_pk_bf16_f32 v35, v38, v39
	s_nop 1
	v_mfma_f32_32x32x16_bf16 v[16:31], v[136:139], v[32:35], v[16:31]
	v_mfma_f32_32x32x16_bf16 v[0:15], v[140:143], v[32:35], v[0:15]
	v_cvt_pk_bf16_f32 v32, v40, v41
	v_cvt_pk_bf16_f32 v33, v42, v43
	v_cvt_pk_bf16_f32 v34, v44, v45
	v_cvt_pk_bf16_f32 v35, v46, v47
	s_nop 1
	v_mfma_f32_32x32x16_bf16 v[16:31], v[128:131], v[32:35], v[16:31]
	v_mfma_f32_32x32x16_bf16 v[0:15], v[132:135], v[32:35], v[0:15]
	s_setprio 0
	v_mov_b32_e32 v227, v189
	v_mov_b32_e32 v228, v188
